# phase 0 adaLN gemv: the 32 weight-row loads per wave issued together with counted waits instead of one load per vmcnt(0)
# speedup vs baseline: 1.0239x; 1.0163x over previous
.LBB0_1246:
	s_or_b64 exec, exec, s[4:5]
	s_add_i32 s4, s35, 0xfffff7a8
	s_lshl_b32 s5, s4, 3
	s_and_b32 s5, s5, 0x1fc0
	s_add_i32 s20, s5, 0xfffff400
	s_cmpk_lt_u32 s4, 0x180
	s_cselect_b32 s50, s5, s20
	s_cmpk_gt_u32 s4, 0x17f
	s_cselect_b64 s[4:5], -1, 0
	s_and_b64 s[20:21], s[4:5], exec
	s_cselect_b32 s20, 0x400, 0
	v_readlane_b32 s76, v252, 42
	s_or_b32 s20, s20, s23
	v_readlane_b32 s80, v252, 46
	v_readlane_b32 s81, v252, 47
	v_add_u32_e32 v0, s20, v34
	s_movk_i32 s23, 0x3000
	v_mov_b64_e32 v[2:3], s[80:81]
	v_mad_i64_i32 v[2:3], s[20:21], v0, s23, v[2:3]
	v_lshl_add_u64 v[2:3], s[50:51], 2, v[2:3]
	v_lshlrev_b32_e32 v0, 2, v26
	v_lshl_add_u64 v[40:41], v[2:3], 0, v[0:1]
	s_waitcnt lgkmcnt(0)
	s_barrier
	s_mov_b32 s21, 0
	global_load_dword v62, v[40:41], off nt
	s_mov_b32 s20, 0x3000
	v_lshl_add_u64 v[96:97], v[40:41], 0, s[20:21]
	global_load_dword v63, v[96:97], off nt
	s_mov_b32 s20, 0x6000
	v_lshl_add_u64 v[98:99], v[40:41], 0, s[20:21]
	global_load_dword v64, v[98:99], off nt
	s_mov_b32 s20, 0x9000
	v_lshl_add_u64 v[100:101], v[40:41], 0, s[20:21]
	global_load_dword v65, v[100:101], off nt
	s_mov_b32 s20, 0xc000
	v_lshl_add_u64 v[94:95], v[40:41], 0, s[20:21]
	global_load_dword v66, v[94:95], off nt
	s_mov_b32 s20, 0xf000
	v_lshl_add_u64 v[96:97], v[40:41], 0, s[20:21]
	global_load_dword v67, v[96:97], off nt
	s_mov_b32 s20, 0x12000
	v_lshl_add_u64 v[98:99], v[40:41], 0, s[20:21]
	global_load_dword v68, v[98:99], off nt
	s_mov_b32 s20, 0x15000
	v_lshl_add_u64 v[100:101], v[40:41], 0, s[20:21]
	global_load_dword v69, v[100:101], off nt
	s_mov_b32 s20, 0x18000
	v_lshl_add_u64 v[94:95], v[40:41], 0, s[20:21]
	global_load_dword v70, v[94:95], off nt
	s_mov_b32 s20, 0x1b000
	v_lshl_add_u64 v[96:97], v[40:41], 0, s[20:21]
	global_load_dword v71, v[96:97], off nt
	s_mov_b32 s20, 0x1e000
	v_lshl_add_u64 v[98:99], v[40:41], 0, s[20:21]
	global_load_dword v72, v[98:99], off nt
	s_mov_b32 s20, 0x21000
	v_lshl_add_u64 v[100:101], v[40:41], 0, s[20:21]
	global_load_dword v73, v[100:101], off nt
	s_mov_b32 s20, 0x24000
	v_lshl_add_u64 v[94:95], v[40:41], 0, s[20:21]
	global_load_dword v74, v[94:95], off nt
	s_mov_b32 s20, 0x27000
	v_lshl_add_u64 v[96:97], v[40:41], 0, s[20:21]
	global_load_dword v75, v[96:97], off nt
	s_mov_b32 s20, 0x2a000
	v_lshl_add_u64 v[98:99], v[40:41], 0, s[20:21]
	global_load_dword v76, v[98:99], off nt
	s_mov_b32 s20, 0x2d000
	v_lshl_add_u64 v[100:101], v[40:41], 0, s[20:21]
	global_load_dword v77, v[100:101], off nt
	s_mov_b32 s20, 0x30000
	v_lshl_add_u64 v[94:95], v[40:41], 0, s[20:21]
	global_load_dword v78, v[94:95], off nt
	s_mov_b32 s20, 0x33000
	v_lshl_add_u64 v[96:97], v[40:41], 0, s[20:21]
	global_load_dword v79, v[96:97], off nt
	s_mov_b32 s20, 0x36000
	v_lshl_add_u64 v[98:99], v[40:41], 0, s[20:21]
	global_load_dword v80, v[98:99], off nt
	s_mov_b32 s20, 0x39000
	v_lshl_add_u64 v[100:101], v[40:41], 0, s[20:21]
	global_load_dword v81, v[100:101], off nt
	s_mov_b32 s20, 0x3c000
	v_lshl_add_u64 v[94:95], v[40:41], 0, s[20:21]
	global_load_dword v82, v[94:95], off nt
	s_mov_b32 s20, 0x3f000
	v_lshl_add_u64 v[96:97], v[40:41], 0, s[20:21]
	global_load_dword v83, v[96:97], off nt
	s_mov_b32 s20, 0x42000
	v_lshl_add_u64 v[98:99], v[40:41], 0, s[20:21]
	global_load_dword v84, v[98:99], off nt
	s_mov_b32 s20, 0x45000
	v_lshl_add_u64 v[100:101], v[40:41], 0, s[20:21]
	global_load_dword v85, v[100:101], off nt
	s_mov_b32 s20, 0x48000
	v_lshl_add_u64 v[94:95], v[40:41], 0, s[20:21]
	global_load_dword v86, v[94:95], off nt
	s_mov_b32 s20, 0x4b000
	v_lshl_add_u64 v[96:97], v[40:41], 0, s[20:21]
	global_load_dword v87, v[96:97], off nt
	s_mov_b32 s20, 0x4e000
	v_lshl_add_u64 v[98:99], v[40:41], 0, s[20:21]
	global_load_dword v88, v[98:99], off nt
	s_mov_b32 s20, 0x51000
	v_lshl_add_u64 v[100:101], v[40:41], 0, s[20:21]
	global_load_dword v89, v[100:101], off nt
	s_mov_b32 s20, 0x54000
	v_lshl_add_u64 v[94:95], v[40:41], 0, s[20:21]
	global_load_dword v90, v[94:95], off nt
	s_mov_b32 s20, 0x57000
	v_lshl_add_u64 v[96:97], v[40:41], 0, s[20:21]
	global_load_dword v91, v[96:97], off nt
	s_mov_b32 s20, 0x5a000
	v_lshl_add_u64 v[98:99], v[40:41], 0, s[20:21]
	global_load_dword v92, v[98:99], off nt
	s_mov_b32 s20, 0x5d000
	v_lshl_add_u64 v[100:101], v[40:41], 0, s[20:21]
	global_load_dword v93, v[100:101], off nt
	ds_read_b128 v[2:5], v43
	ds_read_b128 v[6:9], v43 offset:512
	ds_read_b128 v[10:13], v43 offset:1024
	ds_read_b128 v[14:17], v43 offset:1536
	ds_read_b128 v[18:21], v43 offset:2048
	ds_read_b128 v[104:107], v43 offset:16
	ds_read_b128 v[108:111], v43 offset:528
	ds_read_b128 v[112:115], v43 offset:1040
	ds_read_b128 v[116:119], v43 offset:1552
	ds_read_b128 v[120:123], v43 offset:2064
	v_readlane_b32 s82, v252, 48
	v_readlane_b32 s84, v252, 50
	v_readlane_b32 s77, v252, 43
	v_readlane_b32 s78, v252, 44
	v_readlane_b32 s79, v252, 45
	v_readlane_b32 s83, v252, 49
	v_readlane_b32 s85, v252, 51
	v_readlane_b32 s86, v252, 52
	v_readlane_b32 s87, v252, 53
	v_readlane_b32 s88, v252, 54
	v_readlane_b32 s89, v252, 55
	v_readlane_b32 s90, v252, 56
	v_readlane_b32 s91, v252, 57
	s_waitcnt lgkmcnt(5)
	s_waitcnt vmcnt(31)
	v_fma_f32 v0, v62, v2, 0
	v_fma_f32 v39, v62, v6, 0
	v_fma_f32 v49, v62, v10, 0
	v_fma_f32 v50, v62, v14, 0
	v_fma_f32 v51, v62, v18, 0
	s_waitcnt vmcnt(30)
	v_fmac_f32_e32 v0, v63, v3
	v_fmac_f32_e32 v39, v63, v7
	v_fmac_f32_e32 v49, v63, v11
	v_fmac_f32_e32 v50, v63, v15
	v_fmac_f32_e32 v51, v63, v19
	s_waitcnt vmcnt(29)
	v_fmac_f32_e32 v0, v64, v4
	v_fmac_f32_e32 v39, v64, v8
	v_fmac_f32_e32 v49, v64, v12
	v_fmac_f32_e32 v50, v64, v16
	v_fmac_f32_e32 v51, v64, v20
	s_waitcnt vmcnt(28)
	v_fmac_f32_e32 v0, v65, v5
	v_fmac_f32_e32 v39, v65, v9
	v_fmac_f32_e32 v49, v65, v13
	v_fmac_f32_e32 v50, v65, v17
	v_fmac_f32_e32 v51, v65, v21
	ds_read_b128 v[2:5], v43 offset:32
	ds_read_b128 v[6:9], v43 offset:544
	ds_read_b128 v[10:13], v43 offset:1056
	ds_read_b128 v[14:17], v43 offset:1568
	ds_read_b128 v[18:21], v43 offset:2080
	s_waitcnt lgkmcnt(5)
	s_waitcnt vmcnt(27)
	v_fmac_f32_e32 v0, v66, v104
	v_fmac_f32_e32 v39, v66, v108
	v_fmac_f32_e32 v49, v66, v112
	v_fmac_f32_e32 v50, v66, v116
	v_fmac_f32_e32 v51, v66, v120
	s_waitcnt vmcnt(26)
	v_fmac_f32_e32 v0, v67, v105
	v_fmac_f32_e32 v39, v67, v109
	v_fmac_f32_e32 v49, v67, v113
	v_fmac_f32_e32 v50, v67, v117
	v_fmac_f32_e32 v51, v67, v121
	s_waitcnt vmcnt(25)
	v_fmac_f32_e32 v0, v68, v106
	v_fmac_f32_e32 v39, v68, v110
	v_fmac_f32_e32 v49, v68, v114
	v_fmac_f32_e32 v50, v68, v118
	v_fmac_f32_e32 v51, v68, v122
	s_waitcnt vmcnt(24)
	v_fmac_f32_e32 v0, v69, v107
	v_fmac_f32_e32 v39, v69, v111
	v_fmac_f32_e32 v49, v69, v115
	v_fmac_f32_e32 v50, v69, v119
	v_fmac_f32_e32 v51, v69, v123
	ds_read_b128 v[104:107], v43 offset:48
	ds_read_b128 v[108:111], v43 offset:560
	ds_read_b128 v[112:115], v43 offset:1072
	ds_read_b128 v[116:119], v43 offset:1584
	ds_read_b128 v[120:123], v43 offset:2096
	s_waitcnt lgkmcnt(5)
	s_waitcnt vmcnt(23)
	v_fmac_f32_e32 v0, v70, v2
	v_fmac_f32_e32 v39, v70, v6
	v_fmac_f32_e32 v49, v70, v10
	v_fmac_f32_e32 v50, v70, v14
	v_fmac_f32_e32 v51, v70, v18
	s_waitcnt vmcnt(22)
	v_fmac_f32_e32 v0, v71, v3
	v_fmac_f32_e32 v39, v71, v7
	v_fmac_f32_e32 v49, v71, v11
	v_fmac_f32_e32 v50, v71, v15
	v_fmac_f32_e32 v51, v71, v19
	s_waitcnt vmcnt(21)
	v_fmac_f32_e32 v0, v72, v4
	v_fmac_f32_e32 v39, v72, v8
	v_fmac_f32_e32 v49, v72, v12
	v_fmac_f32_e32 v50, v72, v16
	v_fmac_f32_e32 v51, v72, v20
	s_waitcnt vmcnt(20)
	v_fmac_f32_e32 v0, v73, v5
	v_fmac_f32_e32 v39, v73, v9
	v_fmac_f32_e32 v49, v73, v13
	v_fmac_f32_e32 v50, v73, v17
	v_fmac_f32_e32 v51, v73, v21
	ds_read_b128 v[2:5], v43 offset:64
	ds_read_b128 v[6:9], v43 offset:576
	ds_read_b128 v[10:13], v43 offset:1088
	ds_read_b128 v[14:17], v43 offset:1600
	ds_read_b128 v[18:21], v43 offset:2112
	s_waitcnt lgkmcnt(5)
	s_waitcnt vmcnt(19)
	v_fmac_f32_e32 v0, v74, v104
	v_fmac_f32_e32 v39, v74, v108
	v_fmac_f32_e32 v49, v74, v112
	v_fmac_f32_e32 v50, v74, v116
	v_fmac_f32_e32 v51, v74, v120
	s_waitcnt vmcnt(18)
	v_fmac_f32_e32 v0, v75, v105
	v_fmac_f32_e32 v39, v75, v109
	v_fmac_f32_e32 v49, v75, v113
	v_fmac_f32_e32 v50, v75, v117
	v_fmac_f32_e32 v51, v75, v121
	s_waitcnt vmcnt(17)
	v_fmac_f32_e32 v0, v76, v106
	v_fmac_f32_e32 v39, v76, v110
	v_fmac_f32_e32 v49, v76, v114
	v_fmac_f32_e32 v50, v76, v118
	v_fmac_f32_e32 v51, v76, v122
	s_waitcnt vmcnt(16)
	v_fmac_f32_e32 v0, v77, v107
	v_fmac_f32_e32 v39, v77, v111
	v_fmac_f32_e32 v49, v77, v115
	v_fmac_f32_e32 v50, v77, v119
	v_fmac_f32_e32 v51, v77, v123
	ds_read_b128 v[104:107], v43 offset:80
	ds_read_b128 v[108:111], v43 offset:592
	ds_read_b128 v[112:115], v43 offset:1104
	ds_read_b128 v[116:119], v43 offset:1616
	ds_read_b128 v[120:123], v43 offset:2128
	s_waitcnt lgkmcnt(5)
	s_waitcnt vmcnt(15)
	v_fmac_f32_e32 v0, v78, v2
	v_fmac_f32_e32 v39, v78, v6
	v_fmac_f32_e32 v49, v78, v10
	v_fmac_f32_e32 v50, v78, v14
	v_fmac_f32_e32 v51, v78, v18
	s_waitcnt vmcnt(14)
	v_fmac_f32_e32 v0, v79, v3
	v_fmac_f32_e32 v39, v79, v7
	v_fmac_f32_e32 v49, v79, v11
	v_fmac_f32_e32 v50, v79, v15
	v_fmac_f32_e32 v51, v79, v19
	s_waitcnt vmcnt(13)
	v_fmac_f32_e32 v0, v80, v4
	v_fmac_f32_e32 v39, v80, v8
	v_fmac_f32_e32 v49, v80, v12
	v_fmac_f32_e32 v50, v80, v16
	v_fmac_f32_e32 v51, v80, v20
	s_waitcnt vmcnt(12)
	v_fmac_f32_e32 v0, v81, v5
	v_fmac_f32_e32 v39, v81, v9
	v_fmac_f32_e32 v49, v81, v13
	v_fmac_f32_e32 v50, v81, v17
	v_fmac_f32_e32 v51, v81, v21
	ds_read_b128 v[2:5], v43 offset:96
	ds_read_b128 v[6:9], v43 offset:608
	ds_read_b128 v[10:13], v43 offset:1120
	ds_read_b128 v[14:17], v43 offset:1632
	ds_read_b128 v[18:21], v43 offset:2144
	s_waitcnt lgkmcnt(5)
	s_waitcnt vmcnt(11)
	v_fmac_f32_e32 v0, v82, v104
	v_fmac_f32_e32 v39, v82, v108
	v_fmac_f32_e32 v49, v82, v112
	v_fmac_f32_e32 v50, v82, v116
	v_fmac_f32_e32 v51, v82, v120
	s_waitcnt vmcnt(10)
	v_fmac_f32_e32 v0, v83, v105
	v_fmac_f32_e32 v39, v83, v109
	v_fmac_f32_e32 v49, v83, v113
	v_fmac_f32_e32 v50, v83, v117
	v_fmac_f32_e32 v51, v83, v121
	s_waitcnt vmcnt(9)
	v_fmac_f32_e32 v0, v84, v106
	v_fmac_f32_e32 v39, v84, v110
	v_fmac_f32_e32 v49, v84, v114
	v_fmac_f32_e32 v50, v84, v118
	v_fmac_f32_e32 v51, v84, v122
	s_waitcnt vmcnt(8)
	v_fmac_f32_e32 v0, v85, v107
	v_fmac_f32_e32 v39, v85, v111
	v_fmac_f32_e32 v49, v85, v115
	v_fmac_f32_e32 v50, v85, v119
	v_fmac_f32_e32 v51, v85, v123
	ds_read_b128 v[104:107], v43 offset:112
	ds_read_b128 v[108:111], v43 offset:624
	ds_read_b128 v[112:115], v43 offset:1136
	ds_read_b128 v[116:119], v43 offset:1648
	ds_read_b128 v[120:123], v43 offset:2160
	s_waitcnt lgkmcnt(5)
	s_waitcnt vmcnt(7)
	v_fmac_f32_e32 v0, v86, v2
	v_fmac_f32_e32 v39, v86, v6
	v_fmac_f32_e32 v49, v86, v10
	v_fmac_f32_e32 v50, v86, v14
	v_fmac_f32_e32 v51, v86, v18
	s_waitcnt vmcnt(6)
	v_fmac_f32_e32 v0, v87, v3
	v_fmac_f32_e32 v39, v87, v7
	v_fmac_f32_e32 v49, v87, v11
	v_fmac_f32_e32 v50, v87, v15
	v_fmac_f32_e32 v51, v87, v19
	s_waitcnt vmcnt(5)
	v_fmac_f32_e32 v0, v88, v4
	v_fmac_f32_e32 v39, v88, v8
	v_fmac_f32_e32 v49, v88, v12
	v_fmac_f32_e32 v50, v88, v16
	v_fmac_f32_e32 v51, v88, v20
	s_waitcnt vmcnt(4)
	v_fmac_f32_e32 v0, v89, v5
	v_fmac_f32_e32 v39, v89, v9
	v_fmac_f32_e32 v49, v89, v13
	v_fmac_f32_e32 v50, v89, v17
	v_fmac_f32_e32 v51, v89, v21
	s_waitcnt lgkmcnt(0)
	s_waitcnt vmcnt(3)
	v_fmac_f32_e32 v0, v90, v104
	v_fmac_f32_e32 v39, v90, v108
	v_fmac_f32_e32 v49, v90, v112
	v_fmac_f32_e32 v50, v90, v116
	v_fmac_f32_e32 v51, v90, v120
	s_waitcnt vmcnt(2)
	v_fmac_f32_e32 v0, v91, v105
	v_fmac_f32_e32 v39, v91, v109
	v_fmac_f32_e32 v49, v91, v113
	v_fmac_f32_e32 v50, v91, v117
	v_fmac_f32_e32 v51, v91, v121
	s_waitcnt vmcnt(1)
	v_fmac_f32_e32 v0, v92, v106
	v_fmac_f32_e32 v39, v92, v110
	v_fmac_f32_e32 v49, v92, v114
	v_fmac_f32_e32 v50, v92, v118
	v_fmac_f32_e32 v51, v92, v122
	s_waitcnt vmcnt(0)
	v_fmac_f32_e32 v0, v93, v107
	v_fmac_f32_e32 v39, v93, v111
	v_fmac_f32_e32 v49, v93, v115
	v_fmac_f32_e32 v50, v93, v119
	v_fmac_f32_e32 v51, v93, v123
	ds_write2st64_b32 v47, v0, v39 offset0:10 offset1:11
	ds_write2st64_b32 v47, v49, v50 offset0:12 offset1:13
	ds_write_b32 v47, v51 offset:3584
	s_waitcnt lgkmcnt(0)
	s_barrier
	s_and_saveexec_b64 s[20:21], s[6:7]
	s_movk_i32 s82, 0x1ff
	s_mov_b32 s84, 0x3fb8aa3b
	s_cbranch_execz .LBB0_1134
	s_cmp_eq_u32 s22, 0
	s_cselect_b64 s[22:23], -1, 0
	s_and_b64 s[24:25], s[4:5], exec
	s_cselect_b32 s24, 0xc00, 0
	s_add_i32 s25, s50, s24
	v_readlane_b32 s76, v252, 42
	s_and_b64 s[4:5], s[4:5], exec
	v_or_b32_e32 v0, s25, v26
	v_readlane_b32 s82, v252, 48
	v_readlane_b32 s83, v252, 49
	v_readlane_b32 s84, v252, 50
	s_cselect_b32 s24, 5, 0
	v_lshl_add_u64 v[2:3], s[50:51], 2, v[36:37]
	s_mov_b32 s84, 0x3fb8aa3b
	v_lshl_add_u64 v[4:5], v[0:1], 2, s[82:83]
	s_movk_i32 s82, 0x1ff
	s_mov_b64 s[4:5], 0
	v_mov_b32_e32 v0, v46
	v_mov_b32_e32 v6, v146
	v_readlane_b32 s77, v252, 43
	v_readlane_b32 s78, v252, 44
	v_readlane_b32 s79, v252, 45
	v_readlane_b32 s80, v252, 46
	v_readlane_b32 s81, v252, 47
	v_readlane_b32 s85, v252, 51
	v_readlane_b32 s86, v252, 52
	v_readlane_b32 s87, v252, 53
	v_readlane_b32 s88, v252, 54
	v_readlane_b32 s89, v252, 55
	v_readlane_b32 s90, v252, 56
	v_readlane_b32 s91, v252, 57
	s_branch .LBB0_1249
